# weight-prep latency chains: prep_sc silu loop 16 loads in flight; pe.w1 partial sums 32-row batches instead of serial row loads; adaLN partial-sum items preceded by 4 line-touch loads (phase 0 + layer
# speedup vs baseline: 1.0175x; 1.0175x over previous
.LBB0_13:
	global_load_dword v242, v[2:3], off
	v_lshl_add_u64 v[2:3], v[2:3], 0, s[10:11]
	global_load_dword v243, v[2:3], off
	v_lshl_add_u64 v[2:3], v[2:3], 0, s[10:11]
	global_load_dword v244, v[2:3], off
	v_lshl_add_u64 v[2:3], v[2:3], 0, s[10:11]
	global_load_dword v245, v[2:3], off
	v_lshl_add_u64 v[2:3], v[2:3], 0, s[10:11]
	global_load_dword v246, v[2:3], off
	v_lshl_add_u64 v[2:3], v[2:3], 0, s[10:11]
	global_load_dword v247, v[2:3], off
	v_lshl_add_u64 v[2:3], v[2:3], 0, s[10:11]
	global_load_dword v248, v[2:3], off
	v_lshl_add_u64 v[2:3], v[2:3], 0, s[10:11]
	global_load_dword v249, v[2:3], off
	v_lshl_add_u64 v[2:3], v[2:3], 0, s[10:11]
	global_load_dword v30, v[2:3], off
	v_lshl_add_u64 v[2:3], v[2:3], 0, s[10:11]
	global_load_dword v31, v[2:3], off
	v_lshl_add_u64 v[2:3], v[2:3], 0, s[10:11]
	global_load_dword v32, v[2:3], off
	v_lshl_add_u64 v[2:3], v[2:3], 0, s[10:11]
	global_load_dword v33, v[2:3], off
	v_lshl_add_u64 v[2:3], v[2:3], 0, s[10:11]
	global_load_dword v34, v[2:3], off
	v_lshl_add_u64 v[2:3], v[2:3], 0, s[10:11]
	global_load_dword v35, v[2:3], off
	v_lshl_add_u64 v[2:3], v[2:3], 0, s[10:11]
	global_load_dword v36, v[2:3], off
	v_lshl_add_u64 v[2:3], v[2:3], 0, s[10:11]
	global_load_dword v37, v[2:3], off
	s_waitcnt vmcnt(14)
	v_mul_f32_e32 v7, 0xbfb8aa3b, v242
	v_mul_f32_e32 v4, 0xbfb8aa3b, v243
	v_exp_f32_e32 v7, v7
	v_exp_f32_e32 v4, v4
	v_add_f32_e32 v7, 1.0, v7
	v_add_f32_e32 v4, 1.0, v4
	v_rcp_f32_e32 v7, v7
	v_rcp_f32_e32 v4, v4
	v_mul_f32_e32 v242, v242, v7
	v_mul_f32_e32 v243, v243, v4
	ds_write_b32 v5, v242 offset:0
	ds_write_b32 v5, v243 offset:2048
	s_waitcnt vmcnt(12)
	v_mul_f32_e32 v7, 0xbfb8aa3b, v244
	v_mul_f32_e32 v4, 0xbfb8aa3b, v245
	v_exp_f32_e32 v7, v7
	v_exp_f32_e32 v4, v4
	v_add_f32_e32 v7, 1.0, v7
	v_add_f32_e32 v4, 1.0, v4
	v_rcp_f32_e32 v7, v7
	v_rcp_f32_e32 v4, v4
	v_mul_f32_e32 v244, v244, v7
	v_mul_f32_e32 v245, v245, v4
	ds_write_b32 v5, v244 offset:4096
	ds_write_b32 v5, v245 offset:6144
	s_waitcnt vmcnt(10)
	v_mul_f32_e32 v7, 0xbfb8aa3b, v246
	v_mul_f32_e32 v4, 0xbfb8aa3b, v247
	v_exp_f32_e32 v7, v7
	v_exp_f32_e32 v4, v4
	v_add_f32_e32 v7, 1.0, v7
	v_add_f32_e32 v4, 1.0, v4
	v_rcp_f32_e32 v7, v7
	v_rcp_f32_e32 v4, v4
	v_mul_f32_e32 v246, v246, v7
	v_mul_f32_e32 v247, v247, v4
	ds_write_b32 v5, v246 offset:8192
	ds_write_b32 v5, v247 offset:10240
	s_waitcnt vmcnt(8)
	v_mul_f32_e32 v7, 0xbfb8aa3b, v248
	v_mul_f32_e32 v4, 0xbfb8aa3b, v249
	v_exp_f32_e32 v7, v7
	v_exp_f32_e32 v4, v4
	v_add_f32_e32 v7, 1.0, v7
	v_add_f32_e32 v4, 1.0, v4
	v_rcp_f32_e32 v7, v7
	v_rcp_f32_e32 v4, v4
	v_mul_f32_e32 v248, v248, v7
	v_mul_f32_e32 v249, v249, v4
	ds_write_b32 v5, v248 offset:12288
	ds_write_b32 v5, v249 offset:14336
	s_waitcnt vmcnt(6)
	v_mul_f32_e32 v7, 0xbfb8aa3b, v30
	v_mul_f32_e32 v4, 0xbfb8aa3b, v31
	v_exp_f32_e32 v7, v7
	v_exp_f32_e32 v4, v4
	v_add_f32_e32 v7, 1.0, v7
	v_add_f32_e32 v4, 1.0, v4
	v_rcp_f32_e32 v7, v7
	v_rcp_f32_e32 v4, v4
	v_mul_f32_e32 v30, v30, v7
	v_mul_f32_e32 v31, v31, v4
	ds_write_b32 v5, v30 offset:16384
	ds_write_b32 v5, v31 offset:18432
	s_waitcnt vmcnt(4)
	v_mul_f32_e32 v7, 0xbfb8aa3b, v32
	v_mul_f32_e32 v4, 0xbfb8aa3b, v33
	v_exp_f32_e32 v7, v7
	v_exp_f32_e32 v4, v4
	v_add_f32_e32 v7, 1.0, v7
	v_add_f32_e32 v4, 1.0, v4
	v_rcp_f32_e32 v7, v7
	v_rcp_f32_e32 v4, v4
	v_mul_f32_e32 v32, v32, v7
	v_mul_f32_e32 v33, v33, v4
	ds_write_b32 v5, v32 offset:20480
	ds_write_b32 v5, v33 offset:22528
	s_waitcnt vmcnt(2)
	v_mul_f32_e32 v7, 0xbfb8aa3b, v34
	v_mul_f32_e32 v4, 0xbfb8aa3b, v35
	v_exp_f32_e32 v7, v7
	v_exp_f32_e32 v4, v4
	v_add_f32_e32 v7, 1.0, v7
	v_add_f32_e32 v4, 1.0, v4
	v_rcp_f32_e32 v7, v7
	v_rcp_f32_e32 v4, v4
	v_mul_f32_e32 v34, v34, v7
	v_mul_f32_e32 v35, v35, v4
	ds_write_b32 v5, v34 offset:24576
	ds_write_b32 v5, v35 offset:26624
	s_waitcnt vmcnt(0)
	v_mul_f32_e32 v7, 0xbfb8aa3b, v36
	v_mul_f32_e32 v4, 0xbfb8aa3b, v37
	v_exp_f32_e32 v7, v7
	v_exp_f32_e32 v4, v4
	v_add_f32_e32 v7, 1.0, v7
	v_add_f32_e32 v4, 1.0, v4
	v_rcp_f32_e32 v7, v7
	v_rcp_f32_e32 v4, v4
	v_mul_f32_e32 v36, v36, v7
	v_mul_f32_e32 v37, v37, v4
	ds_write_b32 v5, v36 offset:28672
	ds_write_b32 v5, v37 offset:30720

.LBB0_26:
	s_mov_b32 s88, s22
	s_mov_b32 s89, s26
	s_mov_b64 s[24:25], 0x1000
	global_load_dwordx4 v[162:165], v27, s[88:89]
	global_load_dwordx4 v[166:169], v27, s[88:89] offset:16
	global_load_dwordx4 v[170:173], v27, s[88:89] offset:32
	global_load_dwordx4 v[174:177], v27, s[88:89] offset:48
	global_load_dwordx4 v[178:181], v27, s[88:89] offset:64
	global_load_dwordx4 v[182:185], v27, s[88:89] offset:80
	global_load_dwordx4 v[186:189], v27, s[88:89] offset:96
	global_load_dwordx4 v[190:193], v27, s[88:89] offset:112
	global_load_dword v130, v[2:3], off offset:-2048
	global_load_dword v131, v[2:3], off offset:-1536
	global_load_dword v132, v[2:3], off offset:-1024
	global_load_dword v133, v[2:3], off offset:-512
	global_load_dword v134, v[2:3], off
	global_load_dword v135, v[2:3], off offset:512
	global_load_dword v136, v[2:3], off offset:1024
	global_load_dword v137, v[2:3], off offset:1536
	v_lshl_add_u64 v[2:3], v[2:3], 0, s[24:25]
	global_load_dword v138, v[2:3], off offset:-2048
	global_load_dword v139, v[2:3], off offset:-1536
	global_load_dword v140, v[2:3], off offset:-1024
	global_load_dword v141, v[2:3], off offset:-512
	global_load_dword v142, v[2:3], off
	global_load_dword v143, v[2:3], off offset:512
	global_load_dword v144, v[2:3], off offset:1024
	global_load_dword v145, v[2:3], off offset:1536
	v_lshl_add_u64 v[2:3], v[2:3], 0, s[24:25]
	global_load_dword v146, v[2:3], off offset:-2048
	global_load_dword v147, v[2:3], off offset:-1536
	global_load_dword v148, v[2:3], off offset:-1024
	global_load_dword v149, v[2:3], off offset:-512
	global_load_dword v150, v[2:3], off
	global_load_dword v151, v[2:3], off offset:512
	global_load_dword v152, v[2:3], off offset:1024
	global_load_dword v153, v[2:3], off offset:1536
	v_lshl_add_u64 v[2:3], v[2:3], 0, s[24:25]
	global_load_dword v154, v[2:3], off offset:-2048
	global_load_dword v155, v[2:3], off offset:-1536
	global_load_dword v156, v[2:3], off offset:-1024
	global_load_dword v157, v[2:3], off offset:-512
	global_load_dword v158, v[2:3], off
	global_load_dword v159, v[2:3], off offset:512
	global_load_dword v160, v[2:3], off offset:1024
	global_load_dword v161, v[2:3], off offset:1536
	v_lshl_add_u64 v[2:3], v[2:3], 0, s[24:25]
	s_waitcnt vmcnt(31)
	v_fmac_f32_e32 v4, v162, v130
	s_waitcnt vmcnt(30)
	v_fmac_f32_e32 v4, v163, v131
	s_waitcnt vmcnt(29)
	v_fmac_f32_e32 v4, v164, v132
	s_waitcnt vmcnt(28)
	v_fmac_f32_e32 v4, v165, v133
	s_waitcnt vmcnt(27)
	v_fmac_f32_e32 v4, v166, v134
	s_waitcnt vmcnt(26)
	v_fmac_f32_e32 v4, v167, v135
	s_waitcnt vmcnt(25)
	v_fmac_f32_e32 v4, v168, v136
	s_waitcnt vmcnt(24)
	v_fmac_f32_e32 v4, v169, v137
	s_waitcnt vmcnt(23)
	v_fmac_f32_e32 v4, v170, v138
	s_waitcnt vmcnt(22)
	v_fmac_f32_e32 v4, v171, v139
	s_waitcnt vmcnt(21)
	v_fmac_f32_e32 v4, v172, v140
	s_waitcnt vmcnt(20)
	v_fmac_f32_e32 v4, v173, v141
	s_waitcnt vmcnt(19)
	v_fmac_f32_e32 v4, v174, v142
	s_waitcnt vmcnt(18)
	v_fmac_f32_e32 v4, v175, v143
	s_waitcnt vmcnt(17)
	v_fmac_f32_e32 v4, v176, v144
	s_waitcnt vmcnt(16)
	v_fmac_f32_e32 v4, v177, v145
	s_waitcnt vmcnt(15)
	v_fmac_f32_e32 v4, v178, v146
	s_waitcnt vmcnt(14)
	v_fmac_f32_e32 v4, v179, v147
	s_waitcnt vmcnt(13)
	v_fmac_f32_e32 v4, v180, v148
	s_waitcnt vmcnt(12)
	v_fmac_f32_e32 v4, v181, v149
	s_waitcnt vmcnt(11)
	v_fmac_f32_e32 v4, v182, v150
	s_waitcnt vmcnt(10)
	v_fmac_f32_e32 v4, v183, v151
	s_waitcnt vmcnt(9)
	v_fmac_f32_e32 v4, v184, v152
	s_waitcnt vmcnt(8)
	v_fmac_f32_e32 v4, v185, v153
	s_waitcnt vmcnt(7)
	v_fmac_f32_e32 v4, v186, v154
	s_waitcnt vmcnt(6)
	v_fmac_f32_e32 v4, v187, v155
	s_waitcnt vmcnt(5)
	v_fmac_f32_e32 v4, v188, v156
	s_waitcnt vmcnt(4)
	v_fmac_f32_e32 v4, v189, v157
	s_waitcnt vmcnt(3)
	v_fmac_f32_e32 v4, v190, v158
	s_waitcnt vmcnt(2)
	v_fmac_f32_e32 v4, v191, v159
	s_waitcnt vmcnt(1)
	v_fmac_f32_e32 v4, v192, v160
	s_waitcnt vmcnt(0)
	v_fmac_f32_e32 v4, v193, v161
	global_load_dwordx4 v[162:165], v27, s[88:89] offset:128
	global_load_dwordx4 v[166:169], v27, s[88:89] offset:144
	global_load_dwordx4 v[170:173], v27, s[88:89] offset:160
	global_load_dwordx4 v[174:177], v27, s[88:89] offset:176
	global_load_dwordx4 v[178:181], v27, s[88:89] offset:192
	global_load_dwordx4 v[182:185], v27, s[88:89] offset:208
	global_load_dwordx4 v[186:189], v27, s[88:89] offset:224
	global_load_dwordx4 v[190:193], v27, s[88:89] offset:240
	global_load_dword v130, v[2:3], off offset:-2048
	global_load_dword v131, v[2:3], off offset:-1536
	global_load_dword v132, v[2:3], off offset:-1024
	global_load_dword v133, v[2:3], off offset:-512
	global_load_dword v134, v[2:3], off
	global_load_dword v135, v[2:3], off offset:512
	global_load_dword v136, v[2:3], off offset:1024
	global_load_dword v137, v[2:3], off offset:1536
	v_lshl_add_u64 v[2:3], v[2:3], 0, s[24:25]
	global_load_dword v138, v[2:3], off offset:-2048
	global_load_dword v139, v[2:3], off offset:-1536
	global_load_dword v140, v[2:3], off offset:-1024
	global_load_dword v141, v[2:3], off offset:-512
	global_load_dword v142, v[2:3], off
	global_load_dword v143, v[2:3], off offset:512
	global_load_dword v144, v[2:3], off offset:1024
	global_load_dword v145, v[2:3], off offset:1536
	v_lshl_add_u64 v[2:3], v[2:3], 0, s[24:25]
	global_load_dword v146, v[2:3], off offset:-2048
	global_load_dword v147, v[2:3], off offset:-1536
	global_load_dword v148, v[2:3], off offset:-1024
	global_load_dword v149, v[2:3], off offset:-512
	global_load_dword v150, v[2:3], off
	global_load_dword v151, v[2:3], off offset:512
	global_load_dword v152, v[2:3], off offset:1024
	global_load_dword v153, v[2:3], off offset:1536
	v_lshl_add_u64 v[2:3], v[2:3], 0, s[24:25]
	global_load_dword v154, v[2:3], off offset:-2048
	global_load_dword v155, v[2:3], off offset:-1536
	global_load_dword v156, v[2:3], off offset:-1024
	global_load_dword v157, v[2:3], off offset:-512
	global_load_dword v158, v[2:3], off
	global_load_dword v159, v[2:3], off offset:512
	global_load_dword v160, v[2:3], off offset:1024
	global_load_dword v161, v[2:3], off offset:1536
	v_lshl_add_u64 v[2:3], v[2:3], 0, s[24:25]
	s_waitcnt vmcnt(31)
	v_fmac_f32_e32 v4, v162, v130
	s_waitcnt vmcnt(30)
	v_fmac_f32_e32 v4, v163, v131
	s_waitcnt vmcnt(29)
	v_fmac_f32_e32 v4, v164, v132
	s_waitcnt vmcnt(28)
	v_fmac_f32_e32 v4, v165, v133
	s_waitcnt vmcnt(27)
	v_fmac_f32_e32 v4, v166, v134
	s_waitcnt vmcnt(26)
	v_fmac_f32_e32 v4, v167, v135
	s_waitcnt vmcnt(25)
	v_fmac_f32_e32 v4, v168, v136
	s_waitcnt vmcnt(24)
	v_fmac_f32_e32 v4, v169, v137
	s_waitcnt vmcnt(23)
	v_fmac_f32_e32 v4, v170, v138
	s_waitcnt vmcnt(22)
	v_fmac_f32_e32 v4, v171, v139
	s_waitcnt vmcnt(21)
	v_fmac_f32_e32 v4, v172, v140
	s_waitcnt vmcnt(20)
	v_fmac_f32_e32 v4, v173, v141
	s_waitcnt vmcnt(19)
	v_fmac_f32_e32 v4, v174, v142
	s_waitcnt vmcnt(18)
	v_fmac_f32_e32 v4, v175, v143
	s_waitcnt vmcnt(17)
	v_fmac_f32_e32 v4, v176, v144
	s_waitcnt vmcnt(16)
	v_fmac_f32_e32 v4, v177, v145
	s_waitcnt vmcnt(15)
	v_fmac_f32_e32 v4, v178, v146
	s_waitcnt vmcnt(14)
	v_fmac_f32_e32 v4, v179, v147
	s_waitcnt vmcnt(13)
	v_fmac_f32_e32 v4, v180, v148
	s_waitcnt vmcnt(12)
	v_fmac_f32_e32 v4, v181, v149
	s_waitcnt vmcnt(11)
	v_fmac_f32_e32 v4, v182, v150
	s_waitcnt vmcnt(10)
	v_fmac_f32_e32 v4, v183, v151
	s_waitcnt vmcnt(9)
	v_fmac_f32_e32 v4, v184, v152
	s_waitcnt vmcnt(8)
	v_fmac_f32_e32 v4, v185, v153
	s_waitcnt vmcnt(7)
	v_fmac_f32_e32 v4, v186, v154
	s_waitcnt vmcnt(6)
	v_fmac_f32_e32 v4, v187, v155
	s_waitcnt vmcnt(5)
	v_fmac_f32_e32 v4, v188, v156
	s_waitcnt vmcnt(4)
	v_fmac_f32_e32 v4, v189, v157
	s_waitcnt vmcnt(3)
	v_fmac_f32_e32 v4, v190, v158
	s_waitcnt vmcnt(2)
	v_fmac_f32_e32 v4, v191, v159
	s_waitcnt vmcnt(1)
	v_fmac_f32_e32 v4, v192, v160
	s_waitcnt vmcnt(0)
	v_fmac_f32_e32 v4, v193, v161
	global_load_dwordx4 v[162:165], v27, s[88:89] offset:256
	global_load_dwordx4 v[166:169], v27, s[88:89] offset:272
	global_load_dwordx4 v[170:173], v27, s[88:89] offset:288
	global_load_dwordx4 v[174:177], v27, s[88:89] offset:304
	global_load_dwordx4 v[178:181], v27, s[88:89] offset:320
	global_load_dwordx4 v[182:185], v27, s[88:89] offset:336
	global_load_dwordx4 v[186:189], v27, s[88:89] offset:352
	global_load_dwordx4 v[190:193], v27, s[88:89] offset:368
	global_load_dword v130, v[2:3], off offset:-2048
	global_load_dword v131, v[2:3], off offset:-1536
	global_load_dword v132, v[2:3], off offset:-1024
	global_load_dword v133, v[2:3], off offset:-512
	global_load_dword v134, v[2:3], off
	global_load_dword v135, v[2:3], off offset:512
	global_load_dword v136, v[2:3], off offset:1024
	global_load_dword v137, v[2:3], off offset:1536
	v_lshl_add_u64 v[2:3], v[2:3], 0, s[24:25]
	global_load_dword v138, v[2:3], off offset:-2048
	global_load_dword v139, v[2:3], off offset:-1536
	global_load_dword v140, v[2:3], off offset:-1024
	global_load_dword v141, v[2:3], off offset:-512
	global_load_dword v142, v[2:3], off
	global_load_dword v143, v[2:3], off offset:512
	global_load_dword v144, v[2:3], off offset:1024
	global_load_dword v145, v[2:3], off offset:1536
	v_lshl_add_u64 v[2:3], v[2:3], 0, s[24:25]
	global_load_dword v146, v[2:3], off offset:-2048
	global_load_dword v147, v[2:3], off offset:-1536
	global_load_dword v148, v[2:3], off offset:-1024
	global_load_dword v149, v[2:3], off offset:-512
	global_load_dword v150, v[2:3], off
	global_load_dword v151, v[2:3], off offset:512
	global_load_dword v152, v[2:3], off offset:1024
	global_load_dword v153, v[2:3], off offset:1536
	v_lshl_add_u64 v[2:3], v[2:3], 0, s[24:25]
	global_load_dword v154, v[2:3], off offset:-2048
	global_load_dword v155, v[2:3], off offset:-1536
	global_load_dword v156, v[2:3], off offset:-1024
	global_load_dword v157, v[2:3], off offset:-512
	global_load_dword v158, v[2:3], off
	global_load_dword v159, v[2:3], off offset:512
	global_load_dword v160, v[2:3], off offset:1024
	global_load_dword v161, v[2:3], off offset:1536
	v_lshl_add_u64 v[2:3], v[2:3], 0, s[24:25]
	s_waitcnt vmcnt(31)
	v_fmac_f32_e32 v4, v162, v130
	s_waitcnt vmcnt(30)
	v_fmac_f32_e32 v4, v163, v131
	s_waitcnt vmcnt(29)
	v_fmac_f32_e32 v4, v164, v132
	s_waitcnt vmcnt(28)
	v_fmac_f32_e32 v4, v165, v133
	s_waitcnt vmcnt(27)
	v_fmac_f32_e32 v4, v166, v134
	s_waitcnt vmcnt(26)
	v_fmac_f32_e32 v4, v167, v135
	s_waitcnt vmcnt(25)
	v_fmac_f32_e32 v4, v168, v136
	s_waitcnt vmcnt(24)
	v_fmac_f32_e32 v4, v169, v137
	s_waitcnt vmcnt(23)
	v_fmac_f32_e32 v4, v170, v138
	s_waitcnt vmcnt(22)
	v_fmac_f32_e32 v4, v171, v139
	s_waitcnt vmcnt(21)
	v_fmac_f32_e32 v4, v172, v140
	s_waitcnt vmcnt(20)
	v_fmac_f32_e32 v4, v173, v141
	s_waitcnt vmcnt(19)
	v_fmac_f32_e32 v4, v174, v142
	s_waitcnt vmcnt(18)
	v_fmac_f32_e32 v4, v175, v143
	s_waitcnt vmcnt(17)
	v_fmac_f32_e32 v4, v176, v144
	s_waitcnt vmcnt(16)
	v_fmac_f32_e32 v4, v177, v145
	s_waitcnt vmcnt(15)
	v_fmac_f32_e32 v4, v178, v146
	s_waitcnt vmcnt(14)
	v_fmac_f32_e32 v4, v179, v147
	s_waitcnt vmcnt(13)
	v_fmac_f32_e32 v4, v180, v148
	s_waitcnt vmcnt(12)
	v_fmac_f32_e32 v4, v181, v149
	s_waitcnt vmcnt(11)
	v_fmac_f32_e32 v4, v182, v150
	s_waitcnt vmcnt(10)
	v_fmac_f32_e32 v4, v183, v151
	s_waitcnt vmcnt(9)
	v_fmac_f32_e32 v4, v184, v152
	s_waitcnt vmcnt(8)
	v_fmac_f32_e32 v4, v185, v153
	s_waitcnt vmcnt(7)
	v_fmac_f32_e32 v4, v186, v154
	s_waitcnt vmcnt(6)
	v_fmac_f32_e32 v4, v187, v155
	s_waitcnt vmcnt(5)
	v_fmac_f32_e32 v4, v188, v156
	s_waitcnt vmcnt(4)
	v_fmac_f32_e32 v4, v189, v157
	s_waitcnt vmcnt(3)
	v_fmac_f32_e32 v4, v190, v158
	s_waitcnt vmcnt(2)
	v_fmac_f32_e32 v4, v191, v159
	s_waitcnt vmcnt(1)
	v_fmac_f32_e32 v4, v192, v160
	s_waitcnt vmcnt(0)
	v_fmac_f32_e32 v4, v193, v161
	global_load_dwordx4 v[162:165], v27, s[88:89] offset:384
	global_load_dwordx4 v[166:169], v27, s[88:89] offset:400
	global_load_dwordx4 v[170:173], v27, s[88:89] offset:416
	global_load_dwordx4 v[174:177], v27, s[88:89] offset:432
	global_load_dwordx4 v[178:181], v27, s[88:89] offset:448
	global_load_dwordx4 v[182:185], v27, s[88:89] offset:464
	global_load_dwordx4 v[186:189], v27, s[88:89] offset:480
	global_load_dwordx4 v[190:193], v27, s[88:89] offset:496
	global_load_dword v130, v[2:3], off offset:-2048
	global_load_dword v131, v[2:3], off offset:-1536
	global_load_dword v132, v[2:3], off offset:-1024
	global_load_dword v133, v[2:3], off offset:-512
	global_load_dword v134, v[2:3], off
	global_load_dword v135, v[2:3], off offset:512
	global_load_dword v136, v[2:3], off offset:1024
	global_load_dword v137, v[2:3], off offset:1536
	v_lshl_add_u64 v[2:3], v[2:3], 0, s[24:25]
	global_load_dword v138, v[2:3], off offset:-2048
	global_load_dword v139, v[2:3], off offset:-1536
	global_load_dword v140, v[2:3], off offset:-1024
	global_load_dword v141, v[2:3], off offset:-512
	global_load_dword v142, v[2:3], off
	global_load_dword v143, v[2:3], off offset:512
	global_load_dword v144, v[2:3], off offset:1024
	global_load_dword v145, v[2:3], off offset:1536
	v_lshl_add_u64 v[2:3], v[2:3], 0, s[24:25]
	global_load_dword v146, v[2:3], off offset:-2048
	global_load_dword v147, v[2:3], off offset:-1536
	global_load_dword v148, v[2:3], off offset:-1024
	global_load_dword v149, v[2:3], off offset:-512
	global_load_dword v150, v[2:3], off
	global_load_dword v151, v[2:3], off offset:512
	global_load_dword v152, v[2:3], off offset:1024
	global_load_dword v153, v[2:3], off offset:1536
	v_lshl_add_u64 v[2:3], v[2:3], 0, s[24:25]
	global_load_dword v154, v[2:3], off offset:-2048
	global_load_dword v155, v[2:3], off offset:-1536
	global_load_dword v156, v[2:3], off offset:-1024
	global_load_dword v157, v[2:3], off offset:-512
	global_load_dword v158, v[2:3], off
	global_load_dword v159, v[2:3], off offset:512
	global_load_dword v160, v[2:3], off offset:1024
	global_load_dword v161, v[2:3], off offset:1536
	v_lshl_add_u64 v[2:3], v[2:3], 0, s[24:25]
	s_waitcnt vmcnt(31)
	v_fmac_f32_e32 v4, v162, v130
	s_waitcnt vmcnt(30)
	v_fmac_f32_e32 v4, v163, v131
	s_waitcnt vmcnt(29)
	v_fmac_f32_e32 v4, v164, v132
	s_waitcnt vmcnt(28)
	v_fmac_f32_e32 v4, v165, v133
	s_waitcnt vmcnt(27)
	v_fmac_f32_e32 v4, v166, v134
	s_waitcnt vmcnt(26)
	v_fmac_f32_e32 v4, v167, v135
	s_waitcnt vmcnt(25)
	v_fmac_f32_e32 v4, v168, v136
	s_waitcnt vmcnt(24)
	v_fmac_f32_e32 v4, v169, v137
	s_waitcnt vmcnt(23)
	v_fmac_f32_e32 v4, v170, v138
	s_waitcnt vmcnt(22)
	v_fmac_f32_e32 v4, v171, v139
	s_waitcnt vmcnt(21)
	v_fmac_f32_e32 v4, v172, v140
	s_waitcnt vmcnt(20)
	v_fmac_f32_e32 v4, v173, v141
	s_waitcnt vmcnt(19)
	v_fmac_f32_e32 v4, v174, v142
	s_waitcnt vmcnt(18)
	v_fmac_f32_e32 v4, v175, v143
	s_waitcnt vmcnt(17)
	v_fmac_f32_e32 v4, v176, v144
	s_waitcnt vmcnt(16)
	v_fmac_f32_e32 v4, v177, v145
	s_waitcnt vmcnt(15)
	v_fmac_f32_e32 v4, v178, v146
	s_waitcnt vmcnt(14)
	v_fmac_f32_e32 v4, v179, v147
	s_waitcnt vmcnt(13)
	v_fmac_f32_e32 v4, v180, v148
	s_waitcnt vmcnt(12)
	v_fmac_f32_e32 v4, v181, v149
	s_waitcnt vmcnt(11)
	v_fmac_f32_e32 v4, v182, v150
	s_waitcnt vmcnt(10)
	v_fmac_f32_e32 v4, v183, v151
	s_waitcnt vmcnt(9)
	v_fmac_f32_e32 v4, v184, v152
	s_waitcnt vmcnt(8)
	v_fmac_f32_e32 v4, v185, v153
	s_waitcnt vmcnt(7)
	v_fmac_f32_e32 v4, v186, v154
	s_waitcnt vmcnt(6)
	v_fmac_f32_e32 v4, v187, v155
	s_waitcnt vmcnt(5)
	v_fmac_f32_e32 v4, v188, v156
	s_waitcnt vmcnt(4)
	v_fmac_f32_e32 v4, v189, v157
	s_waitcnt vmcnt(3)
	v_fmac_f32_e32 v4, v190, v158
	s_waitcnt vmcnt(2)
	v_fmac_f32_e32 v4, v191, v159
	s_waitcnt vmcnt(1)
	v_fmac_f32_e32 v4, v192, v160
	s_waitcnt vmcnt(0)
	v_fmac_f32_e32 v4, v193, v161
	s_mov_b64 s[24:25], 0x200
	s_mov_b64 s[88:89], 0x1000
	s_add_i32 s22, s28, 0xffffccf0
	s_lshl_b32 s24, s22, 2
	s_lshl_b32 s25, s28, 7
	s_lshl_b32 s22, s22, 6
	s_and_b32 s25, s25, 0x780
	s_and_b32 s22, s22, 0xfffff800
	s_and_b32 s24, s24, 64
	s_or_b32 s22, s22, s25
	s_or_b32 s22, s22, s24
	v_add_u32_e32 v2, s22, v25
	v_ashrrev_i32_e32 v3, 31, v2
	v_lshl_add_u64 v[2:3], v[2:3], 2, s[18:19]
	s_mov_b64 s[24:25], 0
	global_store_dword v[2:3], v4, off

.LBB0_150:
	s_andn2_b64 vcc, exec, s[0:1]
	s_cbranch_vccnz .LBB0_16
	s_load_dwordx2 s[0:1], s[6:7], 0x10
	s_and_b32 s22, s44, 0xffffffc0
	v_add_u32_e32 v2, s22, v25
	v_mov_b32_e32 v50, 0
	v_ashrrev_i32_e32 v3, 31, v2
	s_waitcnt lgkmcnt(0)
	s_add_u32 s0, s0, s43
	s_addc_u32 s1, s1, 0
	v_lshl_add_u64 v[28:29], v[2:3], 2, s[0:1]
	v_lshrrev_b32_e32 v246, 1, v25
	v_mul_u32_u24_e32 v246, 0x9000, v246
	v_and_b32_e32 v247, 1, v25
	v_lshl_add_u32 v246, v247, 7, v246
	v_lshlrev_b32_e32 v247, 2, v25
	v_sub_u32_e32 v246, v246, v247
	v_mov_b32_e32 v247, 0
	v_lshl_add_u64 v[246:247], v[28:29], 0, v[246:247]
	s_mov_b64 s[24:25], 0x120000
	global_load_dword v242, v[246:247], off
	v_lshl_add_u64 v[246:247], v[246:247], 0, s[24:25]
	global_load_dword v242, v[246:247], off
	v_lshl_add_u64 v[246:247], v[246:247], 0, s[24:25]
	global_load_dword v242, v[246:247], off
	v_lshl_add_u64 v[246:247], v[246:247], 0, s[24:25]
	global_load_dword v242, v[246:247], off
	s_mov_b64 s[24:25], 0
	s_mov_b32 s22, s42
	v_mov_b32_e32 v51, v50
	v_mov_b32_e32 v58, v50
	v_mov_b32_e32 v59, v50
	v_mov_b32_e32 v20, v50
	v_mov_b32_e32 v21, v50
	v_mov_b32_e32 v18, v50
	v_mov_b32_e32 v19, v50

.LBB0_299:
	global_load_dword v242, v[0:1], off
	v_lshl_add_u64 v[0:1], v[0:1], 0, s[8:9]
	global_load_dword v243, v[0:1], off
	v_lshl_add_u64 v[0:1], v[0:1], 0, s[8:9]
	global_load_dword v244, v[0:1], off
	v_lshl_add_u64 v[0:1], v[0:1], 0, s[8:9]
	global_load_dword v245, v[0:1], off
	v_lshl_add_u64 v[0:1], v[0:1], 0, s[8:9]
	global_load_dword v246, v[0:1], off
	v_lshl_add_u64 v[0:1], v[0:1], 0, s[8:9]
	global_load_dword v247, v[0:1], off
	v_lshl_add_u64 v[0:1], v[0:1], 0, s[8:9]
	global_load_dword v248, v[0:1], off
	v_lshl_add_u64 v[0:1], v[0:1], 0, s[8:9]
	global_load_dword v249, v[0:1], off
	v_lshl_add_u64 v[0:1], v[0:1], 0, s[8:9]
	global_load_dword v100, v[0:1], off
	v_lshl_add_u64 v[0:1], v[0:1], 0, s[8:9]
	global_load_dword v101, v[0:1], off
	v_lshl_add_u64 v[0:1], v[0:1], 0, s[8:9]
	global_load_dword v102, v[0:1], off
	v_lshl_add_u64 v[0:1], v[0:1], 0, s[8:9]
	global_load_dword v103, v[0:1], off
	v_lshl_add_u64 v[0:1], v[0:1], 0, s[8:9]
	global_load_dword v104, v[0:1], off
	v_lshl_add_u64 v[0:1], v[0:1], 0, s[8:9]
	global_load_dword v105, v[0:1], off
	v_lshl_add_u64 v[0:1], v[0:1], 0, s[8:9]
	global_load_dword v106, v[0:1], off
	v_lshl_add_u64 v[0:1], v[0:1], 0, s[8:9]
	global_load_dword v107, v[0:1], off
	s_waitcnt vmcnt(14)
	v_mul_f32_e32 v5, 0xbfb8aa3b, v242
	v_mul_f32_e32 v2, 0xbfb8aa3b, v243
	v_exp_f32_e32 v5, v5
	v_exp_f32_e32 v2, v2
	v_add_f32_e32 v5, 1.0, v5
	v_add_f32_e32 v2, 1.0, v2
	v_rcp_f32_e32 v5, v5
	v_rcp_f32_e32 v2, v2
	v_mul_f32_e32 v242, v242, v5
	v_mul_f32_e32 v243, v243, v2
	ds_write_b32 v3, v242 offset:0
	ds_write_b32 v3, v243 offset:2048
	s_waitcnt vmcnt(12)
	v_mul_f32_e32 v5, 0xbfb8aa3b, v244
	v_mul_f32_e32 v2, 0xbfb8aa3b, v245
	v_exp_f32_e32 v5, v5
	v_exp_f32_e32 v2, v2
	v_add_f32_e32 v5, 1.0, v5
	v_add_f32_e32 v2, 1.0, v2
	v_rcp_f32_e32 v5, v5
	v_rcp_f32_e32 v2, v2
	v_mul_f32_e32 v244, v244, v5
	v_mul_f32_e32 v245, v245, v2
	ds_write_b32 v3, v244 offset:4096
	ds_write_b32 v3, v245 offset:6144
	s_waitcnt vmcnt(10)
	v_mul_f32_e32 v5, 0xbfb8aa3b, v246
	v_mul_f32_e32 v2, 0xbfb8aa3b, v247
	v_exp_f32_e32 v5, v5
	v_exp_f32_e32 v2, v2
	v_add_f32_e32 v5, 1.0, v5
	v_add_f32_e32 v2, 1.0, v2
	v_rcp_f32_e32 v5, v5
	v_rcp_f32_e32 v2, v2
	v_mul_f32_e32 v246, v246, v5
	v_mul_f32_e32 v247, v247, v2
	ds_write_b32 v3, v246 offset:8192
	ds_write_b32 v3, v247 offset:10240
	s_waitcnt vmcnt(8)
	v_mul_f32_e32 v5, 0xbfb8aa3b, v248
	v_mul_f32_e32 v2, 0xbfb8aa3b, v249
	v_exp_f32_e32 v5, v5
	v_exp_f32_e32 v2, v2
	v_add_f32_e32 v5, 1.0, v5
	v_add_f32_e32 v2, 1.0, v2
	v_rcp_f32_e32 v5, v5
	v_rcp_f32_e32 v2, v2
	v_mul_f32_e32 v248, v248, v5
	v_mul_f32_e32 v249, v249, v2
	ds_write_b32 v3, v248 offset:12288
	ds_write_b32 v3, v249 offset:14336
	s_waitcnt vmcnt(6)
	v_mul_f32_e32 v5, 0xbfb8aa3b, v100
	v_mul_f32_e32 v2, 0xbfb8aa3b, v101
	v_exp_f32_e32 v5, v5
	v_exp_f32_e32 v2, v2
	v_add_f32_e32 v5, 1.0, v5
	v_add_f32_e32 v2, 1.0, v2
	v_rcp_f32_e32 v5, v5
	v_rcp_f32_e32 v2, v2
	v_mul_f32_e32 v100, v100, v5
	v_mul_f32_e32 v101, v101, v2
	ds_write_b32 v3, v100 offset:16384
	ds_write_b32 v3, v101 offset:18432
	s_waitcnt vmcnt(4)
	v_mul_f32_e32 v5, 0xbfb8aa3b, v102
	v_mul_f32_e32 v2, 0xbfb8aa3b, v103
	v_exp_f32_e32 v5, v5
	v_exp_f32_e32 v2, v2
	v_add_f32_e32 v5, 1.0, v5
	v_add_f32_e32 v2, 1.0, v2
	v_rcp_f32_e32 v5, v5
	v_rcp_f32_e32 v2, v2
	v_mul_f32_e32 v102, v102, v5
	v_mul_f32_e32 v103, v103, v2
	ds_write_b32 v3, v102 offset:20480
	ds_write_b32 v3, v103 offset:22528
	s_waitcnt vmcnt(2)
	v_mul_f32_e32 v5, 0xbfb8aa3b, v104
	v_mul_f32_e32 v2, 0xbfb8aa3b, v105
	v_exp_f32_e32 v5, v5
	v_exp_f32_e32 v2, v2
	v_add_f32_e32 v5, 1.0, v5
	v_add_f32_e32 v2, 1.0, v2
	v_rcp_f32_e32 v5, v5
	v_rcp_f32_e32 v2, v2
	v_mul_f32_e32 v104, v104, v5
	v_mul_f32_e32 v105, v105, v2
	ds_write_b32 v3, v104 offset:24576
	ds_write_b32 v3, v105 offset:26624
	s_waitcnt vmcnt(0)
	v_mul_f32_e32 v5, 0xbfb8aa3b, v106
	v_mul_f32_e32 v2, 0xbfb8aa3b, v107
	v_exp_f32_e32 v5, v5
	v_exp_f32_e32 v2, v2
	v_add_f32_e32 v5, 1.0, v5
	v_add_f32_e32 v2, 1.0, v2
	v_rcp_f32_e32 v5, v5
	v_rcp_f32_e32 v2, v2
	v_mul_f32_e32 v106, v106, v5
	v_mul_f32_e32 v107, v107, v2
	ds_write_b32 v3, v106 offset:28672
	ds_write_b32 v3, v107 offset:30720

.LBB0_329:
	s_and_b64 vcc, exec, s[4:5]
	s_cbranch_vccz .LBB0_302
	s_load_dwordx2 s[4:5], s[2:3], 0x10
	s_and_b32 s6, s14, 0xffffffc0
	v_add_u32_e32 v0, s6, v166
	v_mov_b32_e32 v24, 0
	v_ashrrev_i32_e32 v1, 31, v0
	s_waitcnt lgkmcnt(0)
	s_add_u32 s4, s4, s13
	s_addc_u32 s5, s5, 0
	v_lshl_add_u64 v[26:27], v[0:1], 2, s[4:5]
	v_lshrrev_b32_e32 v246, 1, v166
	v_mul_u32_u24_e32 v246, 0x9000, v246
	v_and_b32_e32 v247, 1, v166
	v_lshl_add_u32 v246, v247, 7, v246
	v_lshlrev_b32_e32 v247, 2, v166
	v_sub_u32_e32 v246, v246, v247
	v_add_u32_e32 v246, 0x2400000, v246
	v_mov_b32_e32 v247, 0
	v_lshl_add_u64 v[246:247], v[26:27], 0, v[246:247]
	s_mov_b64 s[4:5], 0x120000
	global_load_dword v242, v[246:247], off
	v_lshl_add_u64 v[246:247], v[246:247], 0, s[4:5]
	global_load_dword v242, v[246:247], off
	v_lshl_add_u64 v[246:247], v[246:247], 0, s[4:5]
	global_load_dword v242, v[246:247], off
	v_lshl_add_u64 v[246:247], v[246:247], 0, s[4:5]
	global_load_dword v242, v[246:247], off
	s_mov_b64 s[4:5], 0
	s_mov_b32 s6, s12
	v_mov_b32_e32 v25, v24
	v_mov_b32_e32 v32, v24
	v_mov_b32_e32 v33, v24
	v_mov_b32_e32 v30, v24
	v_mov_b32_e32 v31, v24
	v_mov_b32_e32 v28, v24
	v_mov_b32_e32 v29, v24

.LBB0_722:
	global_load_dword v242, v[0:1], off
	v_lshl_add_u64 v[0:1], v[0:1], 0, s[6:7]
	global_load_dword v243, v[0:1], off
	v_lshl_add_u64 v[0:1], v[0:1], 0, s[6:7]
	global_load_dword v244, v[0:1], off
	v_lshl_add_u64 v[0:1], v[0:1], 0, s[6:7]
	global_load_dword v245, v[0:1], off
	v_lshl_add_u64 v[0:1], v[0:1], 0, s[6:7]
	global_load_dword v246, v[0:1], off
	v_lshl_add_u64 v[0:1], v[0:1], 0, s[6:7]
	global_load_dword v247, v[0:1], off
	v_lshl_add_u64 v[0:1], v[0:1], 0, s[6:7]
	global_load_dword v248, v[0:1], off
	v_lshl_add_u64 v[0:1], v[0:1], 0, s[6:7]
	global_load_dword v249, v[0:1], off
	v_lshl_add_u64 v[0:1], v[0:1], 0, s[6:7]
	global_load_dword v100, v[0:1], off
	v_lshl_add_u64 v[0:1], v[0:1], 0, s[6:7]
	global_load_dword v101, v[0:1], off
	v_lshl_add_u64 v[0:1], v[0:1], 0, s[6:7]
	global_load_dword v102, v[0:1], off
	v_lshl_add_u64 v[0:1], v[0:1], 0, s[6:7]
	global_load_dword v103, v[0:1], off
	v_lshl_add_u64 v[0:1], v[0:1], 0, s[6:7]
	global_load_dword v104, v[0:1], off
	v_lshl_add_u64 v[0:1], v[0:1], 0, s[6:7]
	global_load_dword v105, v[0:1], off
	v_lshl_add_u64 v[0:1], v[0:1], 0, s[6:7]
	global_load_dword v106, v[0:1], off
	v_lshl_add_u64 v[0:1], v[0:1], 0, s[6:7]
	global_load_dword v107, v[0:1], off
	s_waitcnt vmcnt(14)
	v_mul_f32_e32 v5, 0xbfb8aa3b, v242
	v_mul_f32_e32 v2, 0xbfb8aa3b, v243
	v_exp_f32_e32 v5, v5
	v_exp_f32_e32 v2, v2
	v_add_f32_e32 v5, 1.0, v5
	v_add_f32_e32 v2, 1.0, v2
	v_rcp_f32_e32 v5, v5
	v_rcp_f32_e32 v2, v2
	v_mul_f32_e32 v242, v242, v5
	v_mul_f32_e32 v243, v243, v2
	ds_write_b32 v3, v242 offset:0
	ds_write_b32 v3, v243 offset:2048
	s_waitcnt vmcnt(12)
	v_mul_f32_e32 v5, 0xbfb8aa3b, v244
	v_mul_f32_e32 v2, 0xbfb8aa3b, v245
	v_exp_f32_e32 v5, v5
	v_exp_f32_e32 v2, v2
	v_add_f32_e32 v5, 1.0, v5
	v_add_f32_e32 v2, 1.0, v2
	v_rcp_f32_e32 v5, v5
	v_rcp_f32_e32 v2, v2
	v_mul_f32_e32 v244, v244, v5
	v_mul_f32_e32 v245, v245, v2
	ds_write_b32 v3, v244 offset:4096
	ds_write_b32 v3, v245 offset:6144
	s_waitcnt vmcnt(10)
	v_mul_f32_e32 v5, 0xbfb8aa3b, v246
	v_mul_f32_e32 v2, 0xbfb8aa3b, v247
	v_exp_f32_e32 v5, v5
	v_exp_f32_e32 v2, v2
	v_add_f32_e32 v5, 1.0, v5
	v_add_f32_e32 v2, 1.0, v2
	v_rcp_f32_e32 v5, v5
	v_rcp_f32_e32 v2, v2
	v_mul_f32_e32 v246, v246, v5
	v_mul_f32_e32 v247, v247, v2
	ds_write_b32 v3, v246 offset:8192
	ds_write_b32 v3, v247 offset:10240
	s_waitcnt vmcnt(8)
	v_mul_f32_e32 v5, 0xbfb8aa3b, v248
	v_mul_f32_e32 v2, 0xbfb8aa3b, v249
	v_exp_f32_e32 v5, v5
	v_exp_f32_e32 v2, v2
	v_add_f32_e32 v5, 1.0, v5
	v_add_f32_e32 v2, 1.0, v2
	v_rcp_f32_e32 v5, v5
	v_rcp_f32_e32 v2, v2
	v_mul_f32_e32 v248, v248, v5
	v_mul_f32_e32 v249, v249, v2
	ds_write_b32 v3, v248 offset:12288
	ds_write_b32 v3, v249 offset:14336
	s_waitcnt vmcnt(6)
	v_mul_f32_e32 v5, 0xbfb8aa3b, v100
	v_mul_f32_e32 v2, 0xbfb8aa3b, v101
	v_exp_f32_e32 v5, v5
	v_exp_f32_e32 v2, v2
	v_add_f32_e32 v5, 1.0, v5
	v_add_f32_e32 v2, 1.0, v2
	v_rcp_f32_e32 v5, v5
	v_rcp_f32_e32 v2, v2
	v_mul_f32_e32 v100, v100, v5
	v_mul_f32_e32 v101, v101, v2
	ds_write_b32 v3, v100 offset:16384
	ds_write_b32 v3, v101 offset:18432
	s_waitcnt vmcnt(4)
	v_mul_f32_e32 v5, 0xbfb8aa3b, v102
	v_mul_f32_e32 v2, 0xbfb8aa3b, v103
	v_exp_f32_e32 v5, v5
	v_exp_f32_e32 v2, v2
	v_add_f32_e32 v5, 1.0, v5
	v_add_f32_e32 v2, 1.0, v2
	v_rcp_f32_e32 v5, v5
	v_rcp_f32_e32 v2, v2
	v_mul_f32_e32 v102, v102, v5
	v_mul_f32_e32 v103, v103, v2
	ds_write_b32 v3, v102 offset:20480
	ds_write_b32 v3, v103 offset:22528
	s_waitcnt vmcnt(2)
	v_mul_f32_e32 v5, 0xbfb8aa3b, v104
	v_mul_f32_e32 v2, 0xbfb8aa3b, v105
	v_exp_f32_e32 v5, v5
	v_exp_f32_e32 v2, v2
	v_add_f32_e32 v5, 1.0, v5
	v_add_f32_e32 v2, 1.0, v2
	v_rcp_f32_e32 v5, v5
	v_rcp_f32_e32 v2, v2
	v_mul_f32_e32 v104, v104, v5
	v_mul_f32_e32 v105, v105, v2
	ds_write_b32 v3, v104 offset:24576
	ds_write_b32 v3, v105 offset:26624
	s_waitcnt vmcnt(0)
	v_mul_f32_e32 v5, 0xbfb8aa3b, v106
	v_mul_f32_e32 v2, 0xbfb8aa3b, v107
	v_exp_f32_e32 v5, v5
	v_exp_f32_e32 v2, v2
	v_add_f32_e32 v5, 1.0, v5
	v_add_f32_e32 v2, 1.0, v2
	v_rcp_f32_e32 v5, v5
	v_rcp_f32_e32 v2, v2
	v_mul_f32_e32 v106, v106, v5
	v_mul_f32_e32 v107, v107, v2
	ds_write_b32 v3, v106 offset:28672
	ds_write_b32 v3, v107 offset:30720

.LBB0_1276:
	s_mov_b32 s86, s16
	s_mov_b32 s87, s24
	global_load_dwordx4 v[210:213], v3, s[86:87]
	global_load_dwordx4 v[214:217], v3, s[86:87] offset:16
	global_load_dwordx4 v[218:221], v3, s[86:87] offset:32
	global_load_dwordx4 v[222:225], v3, s[86:87] offset:48
	global_load_dwordx4 v[226:229], v3, s[86:87] offset:64
	global_load_dwordx4 v[230:233], v3, s[86:87] offset:80
	global_load_dwordx4 v[234:237], v3, s[86:87] offset:96
	global_load_dwordx4 v[238:241], v3, s[86:87] offset:112
	global_load_dword v168, v[4:5], off offset:-2048
	global_load_dword v169, v[4:5], off offset:-1536
	global_load_dword v170, v[4:5], off offset:-1024
	global_load_dword v171, v[4:5], off offset:-512
	global_load_dword v172, v[4:5], off
	global_load_dword v173, v[4:5], off offset:512
	global_load_dword v174, v[4:5], off offset:1024
	global_load_dword v175, v[4:5], off offset:1536
	v_lshl_add_u64 v[4:5], v[4:5], 0, s[20:21]
	global_load_dword v176, v[4:5], off offset:-2048
	global_load_dword v177, v[4:5], off offset:-1536
	global_load_dword v178, v[4:5], off offset:-1024
	global_load_dword v179, v[4:5], off offset:-512
	global_load_dword v180, v[4:5], off
	global_load_dword v181, v[4:5], off offset:512
	global_load_dword v182, v[4:5], off offset:1024
	global_load_dword v183, v[4:5], off offset:1536
	v_lshl_add_u64 v[4:5], v[4:5], 0, s[20:21]
	global_load_dword v184, v[4:5], off offset:-2048
	global_load_dword v185, v[4:5], off offset:-1536
	global_load_dword v186, v[4:5], off offset:-1024
	global_load_dword v187, v[4:5], off offset:-512
	global_load_dword v188, v[4:5], off
	global_load_dword v189, v[4:5], off offset:512
	global_load_dword v190, v[4:5], off offset:1024
	global_load_dword v191, v[4:5], off offset:1536
	v_lshl_add_u64 v[4:5], v[4:5], 0, s[20:21]
	global_load_dword v192, v[4:5], off offset:-2048
	global_load_dword v193, v[4:5], off offset:-1536
	global_load_dword v194, v[4:5], off offset:-1024
	global_load_dword v195, v[4:5], off offset:-512
	global_load_dword v196, v[4:5], off
	global_load_dword v197, v[4:5], off offset:512
	global_load_dword v198, v[4:5], off offset:1024
	global_load_dword v199, v[4:5], off offset:1536
	v_lshl_add_u64 v[4:5], v[4:5], 0, s[20:21]
	s_waitcnt vmcnt(31)
	v_fmac_f32_e32 v2, v210, v168
	s_waitcnt vmcnt(30)
	v_fmac_f32_e32 v2, v211, v169
	s_waitcnt vmcnt(29)
	v_fmac_f32_e32 v2, v212, v170
	s_waitcnt vmcnt(28)
	v_fmac_f32_e32 v2, v213, v171
	s_waitcnt vmcnt(27)
	v_fmac_f32_e32 v2, v214, v172
	s_waitcnt vmcnt(26)
	v_fmac_f32_e32 v2, v215, v173
	s_waitcnt vmcnt(25)
	v_fmac_f32_e32 v2, v216, v174
	s_waitcnt vmcnt(24)
	v_fmac_f32_e32 v2, v217, v175
	s_waitcnt vmcnt(23)
	v_fmac_f32_e32 v2, v218, v176
	s_waitcnt vmcnt(22)
	v_fmac_f32_e32 v2, v219, v177
	s_waitcnt vmcnt(21)
	v_fmac_f32_e32 v2, v220, v178
	s_waitcnt vmcnt(20)
	v_fmac_f32_e32 v2, v221, v179
	s_waitcnt vmcnt(19)
	v_fmac_f32_e32 v2, v222, v180
	s_waitcnt vmcnt(18)
	v_fmac_f32_e32 v2, v223, v181
	s_waitcnt vmcnt(17)
	v_fmac_f32_e32 v2, v224, v182
	s_waitcnt vmcnt(16)
	v_fmac_f32_e32 v2, v225, v183
	s_waitcnt vmcnt(15)
	v_fmac_f32_e32 v2, v226, v184
	s_waitcnt vmcnt(14)
	v_fmac_f32_e32 v2, v227, v185
	s_waitcnt vmcnt(13)
	v_fmac_f32_e32 v2, v228, v186
	s_waitcnt vmcnt(12)
	v_fmac_f32_e32 v2, v229, v187
	s_waitcnt vmcnt(11)
	v_fmac_f32_e32 v2, v230, v188
	s_waitcnt vmcnt(10)
	v_fmac_f32_e32 v2, v231, v189
	s_waitcnt vmcnt(9)
	v_fmac_f32_e32 v2, v232, v190
	s_waitcnt vmcnt(8)
	v_fmac_f32_e32 v2, v233, v191
	s_waitcnt vmcnt(7)
	v_fmac_f32_e32 v2, v234, v192
	s_waitcnt vmcnt(6)
	v_fmac_f32_e32 v2, v235, v193
	s_waitcnt vmcnt(5)
	v_fmac_f32_e32 v2, v236, v194
	s_waitcnt vmcnt(4)
	v_fmac_f32_e32 v2, v237, v195
	s_waitcnt vmcnt(3)
	v_fmac_f32_e32 v2, v238, v196
	s_waitcnt vmcnt(2)
	v_fmac_f32_e32 v2, v239, v197
	s_waitcnt vmcnt(1)
	v_fmac_f32_e32 v2, v240, v198
	s_waitcnt vmcnt(0)
	v_fmac_f32_e32 v2, v241, v199
	global_load_dwordx4 v[210:213], v3, s[86:87] offset:128
	global_load_dwordx4 v[214:217], v3, s[86:87] offset:144
	global_load_dwordx4 v[218:221], v3, s[86:87] offset:160
	global_load_dwordx4 v[222:225], v3, s[86:87] offset:176
	global_load_dwordx4 v[226:229], v3, s[86:87] offset:192
	global_load_dwordx4 v[230:233], v3, s[86:87] offset:208
	global_load_dwordx4 v[234:237], v3, s[86:87] offset:224
	global_load_dwordx4 v[238:241], v3, s[86:87] offset:240
	global_load_dword v168, v[4:5], off offset:-2048
	global_load_dword v169, v[4:5], off offset:-1536
	global_load_dword v170, v[4:5], off offset:-1024
	global_load_dword v171, v[4:5], off offset:-512
	global_load_dword v172, v[4:5], off
	global_load_dword v173, v[4:5], off offset:512
	global_load_dword v174, v[4:5], off offset:1024
	global_load_dword v175, v[4:5], off offset:1536
	v_lshl_add_u64 v[4:5], v[4:5], 0, s[20:21]
	global_load_dword v176, v[4:5], off offset:-2048
	global_load_dword v177, v[4:5], off offset:-1536
	global_load_dword v178, v[4:5], off offset:-1024
	global_load_dword v179, v[4:5], off offset:-512
	global_load_dword v180, v[4:5], off
	global_load_dword v181, v[4:5], off offset:512
	global_load_dword v182, v[4:5], off offset:1024
	global_load_dword v183, v[4:5], off offset:1536
	v_lshl_add_u64 v[4:5], v[4:5], 0, s[20:21]
	global_load_dword v184, v[4:5], off offset:-2048
	global_load_dword v185, v[4:5], off offset:-1536
	global_load_dword v186, v[4:5], off offset:-1024
	global_load_dword v187, v[4:5], off offset:-512
	global_load_dword v188, v[4:5], off
	global_load_dword v189, v[4:5], off offset:512
	global_load_dword v190, v[4:5], off offset:1024
	global_load_dword v191, v[4:5], off offset:1536
	v_lshl_add_u64 v[4:5], v[4:5], 0, s[20:21]
	global_load_dword v192, v[4:5], off offset:-2048
	global_load_dword v193, v[4:5], off offset:-1536
	global_load_dword v194, v[4:5], off offset:-1024
	global_load_dword v195, v[4:5], off offset:-512
	global_load_dword v196, v[4:5], off
	global_load_dword v197, v[4:5], off offset:512
	global_load_dword v198, v[4:5], off offset:1024
	global_load_dword v199, v[4:5], off offset:1536
	v_lshl_add_u64 v[4:5], v[4:5], 0, s[20:21]
	s_waitcnt vmcnt(31)
	v_fmac_f32_e32 v2, v210, v168
	s_waitcnt vmcnt(30)
	v_fmac_f32_e32 v2, v211, v169
	s_waitcnt vmcnt(29)
	v_fmac_f32_e32 v2, v212, v170
	s_waitcnt vmcnt(28)
	v_fmac_f32_e32 v2, v213, v171
	s_waitcnt vmcnt(27)
	v_fmac_f32_e32 v2, v214, v172
	s_waitcnt vmcnt(26)
	v_fmac_f32_e32 v2, v215, v173
	s_waitcnt vmcnt(25)
	v_fmac_f32_e32 v2, v216, v174
	s_waitcnt vmcnt(24)
	v_fmac_f32_e32 v2, v217, v175
	s_waitcnt vmcnt(23)
	v_fmac_f32_e32 v2, v218, v176
	s_waitcnt vmcnt(22)
	v_fmac_f32_e32 v2, v219, v177
	s_waitcnt vmcnt(21)
	v_fmac_f32_e32 v2, v220, v178
	s_waitcnt vmcnt(20)
	v_fmac_f32_e32 v2, v221, v179
	s_waitcnt vmcnt(19)
	v_fmac_f32_e32 v2, v222, v180
	s_waitcnt vmcnt(18)
	v_fmac_f32_e32 v2, v223, v181
	s_waitcnt vmcnt(17)
	v_fmac_f32_e32 v2, v224, v182
	s_waitcnt vmcnt(16)
	v_fmac_f32_e32 v2, v225, v183
	s_waitcnt vmcnt(15)
	v_fmac_f32_e32 v2, v226, v184
	s_waitcnt vmcnt(14)
	v_fmac_f32_e32 v2, v227, v185
	s_waitcnt vmcnt(13)
	v_fmac_f32_e32 v2, v228, v186
	s_waitcnt vmcnt(12)
	v_fmac_f32_e32 v2, v229, v187
	s_waitcnt vmcnt(11)
	v_fmac_f32_e32 v2, v230, v188
	s_waitcnt vmcnt(10)
	v_fmac_f32_e32 v2, v231, v189
	s_waitcnt vmcnt(9)
	v_fmac_f32_e32 v2, v232, v190
	s_waitcnt vmcnt(8)
	v_fmac_f32_e32 v2, v233, v191
	s_waitcnt vmcnt(7)
	v_fmac_f32_e32 v2, v234, v192
	s_waitcnt vmcnt(6)
	v_fmac_f32_e32 v2, v235, v193
	s_waitcnt vmcnt(5)
	v_fmac_f32_e32 v2, v236, v194
	s_waitcnt vmcnt(4)
	v_fmac_f32_e32 v2, v237, v195
	s_waitcnt vmcnt(3)
	v_fmac_f32_e32 v2, v238, v196
	s_waitcnt vmcnt(2)
	v_fmac_f32_e32 v2, v239, v197
	s_waitcnt vmcnt(1)
	v_fmac_f32_e32 v2, v240, v198
	s_waitcnt vmcnt(0)
	v_fmac_f32_e32 v2, v241, v199
	global_load_dwordx4 v[210:213], v3, s[86:87] offset:256
	global_load_dwordx4 v[214:217], v3, s[86:87] offset:272
	global_load_dwordx4 v[218:221], v3, s[86:87] offset:288
	global_load_dwordx4 v[222:225], v3, s[86:87] offset:304
	global_load_dwordx4 v[226:229], v3, s[86:87] offset:320
	global_load_dwordx4 v[230:233], v3, s[86:87] offset:336
	global_load_dwordx4 v[234:237], v3, s[86:87] offset:352
	global_load_dwordx4 v[238:241], v3, s[86:87] offset:368
	global_load_dword v168, v[4:5], off offset:-2048
	global_load_dword v169, v[4:5], off offset:-1536
	global_load_dword v170, v[4:5], off offset:-1024
	global_load_dword v171, v[4:5], off offset:-512
	global_load_dword v172, v[4:5], off
	global_load_dword v173, v[4:5], off offset:512
	global_load_dword v174, v[4:5], off offset:1024
	global_load_dword v175, v[4:5], off offset:1536
	v_lshl_add_u64 v[4:5], v[4:5], 0, s[20:21]
	global_load_dword v176, v[4:5], off offset:-2048
	global_load_dword v177, v[4:5], off offset:-1536
	global_load_dword v178, v[4:5], off offset:-1024
	global_load_dword v179, v[4:5], off offset:-512
	global_load_dword v180, v[4:5], off
	global_load_dword v181, v[4:5], off offset:512
	global_load_dword v182, v[4:5], off offset:1024
	global_load_dword v183, v[4:5], off offset:1536
	v_lshl_add_u64 v[4:5], v[4:5], 0, s[20:21]
	global_load_dword v184, v[4:5], off offset:-2048
	global_load_dword v185, v[4:5], off offset:-1536
	global_load_dword v186, v[4:5], off offset:-1024
	global_load_dword v187, v[4:5], off offset:-512
	global_load_dword v188, v[4:5], off
	global_load_dword v189, v[4:5], off offset:512
	global_load_dword v190, v[4:5], off offset:1024
	global_load_dword v191, v[4:5], off offset:1536
	v_lshl_add_u64 v[4:5], v[4:5], 0, s[20:21]
	global_load_dword v192, v[4:5], off offset:-2048
	global_load_dword v193, v[4:5], off offset:-1536
	global_load_dword v194, v[4:5], off offset:-1024
	global_load_dword v195, v[4:5], off offset:-512
	global_load_dword v196, v[4:5], off
	global_load_dword v197, v[4:5], off offset:512
	global_load_dword v198, v[4:5], off offset:1024
	global_load_dword v199, v[4:5], off offset:1536
	v_lshl_add_u64 v[4:5], v[4:5], 0, s[20:21]
	s_waitcnt vmcnt(31)
	v_fmac_f32_e32 v2, v210, v168
	s_waitcnt vmcnt(30)
	v_fmac_f32_e32 v2, v211, v169
	s_waitcnt vmcnt(29)
	v_fmac_f32_e32 v2, v212, v170
	s_waitcnt vmcnt(28)
	v_fmac_f32_e32 v2, v213, v171
	s_waitcnt vmcnt(27)
	v_fmac_f32_e32 v2, v214, v172
	s_waitcnt vmcnt(26)
	v_fmac_f32_e32 v2, v215, v173
	s_waitcnt vmcnt(25)
	v_fmac_f32_e32 v2, v216, v174
	s_waitcnt vmcnt(24)
	v_fmac_f32_e32 v2, v217, v175
	s_waitcnt vmcnt(23)
	v_fmac_f32_e32 v2, v218, v176
	s_waitcnt vmcnt(22)
	v_fmac_f32_e32 v2, v219, v177
	s_waitcnt vmcnt(21)
	v_fmac_f32_e32 v2, v220, v178
	s_waitcnt vmcnt(20)
	v_fmac_f32_e32 v2, v221, v179
	s_waitcnt vmcnt(19)
	v_fmac_f32_e32 v2, v222, v180
	s_waitcnt vmcnt(18)
	v_fmac_f32_e32 v2, v223, v181
	s_waitcnt vmcnt(17)
	v_fmac_f32_e32 v2, v224, v182
	s_waitcnt vmcnt(16)
	v_fmac_f32_e32 v2, v225, v183
	s_waitcnt vmcnt(15)
	v_fmac_f32_e32 v2, v226, v184
	s_waitcnt vmcnt(14)
	v_fmac_f32_e32 v2, v227, v185
	s_waitcnt vmcnt(13)
	v_fmac_f32_e32 v2, v228, v186
	s_waitcnt vmcnt(12)
	v_fmac_f32_e32 v2, v229, v187
	s_waitcnt vmcnt(11)
	v_fmac_f32_e32 v2, v230, v188
	s_waitcnt vmcnt(10)
	v_fmac_f32_e32 v2, v231, v189
	s_waitcnt vmcnt(9)
	v_fmac_f32_e32 v2, v232, v190
	s_waitcnt vmcnt(8)
	v_fmac_f32_e32 v2, v233, v191
	s_waitcnt vmcnt(7)
	v_fmac_f32_e32 v2, v234, v192
	s_waitcnt vmcnt(6)
	v_fmac_f32_e32 v2, v235, v193
	s_waitcnt vmcnt(5)
	v_fmac_f32_e32 v2, v236, v194
	s_waitcnt vmcnt(4)
	v_fmac_f32_e32 v2, v237, v195
	s_waitcnt vmcnt(3)
	v_fmac_f32_e32 v2, v238, v196
	s_waitcnt vmcnt(2)
	v_fmac_f32_e32 v2, v239, v197
	s_waitcnt vmcnt(1)
	v_fmac_f32_e32 v2, v240, v198
	s_waitcnt vmcnt(0)
	v_fmac_f32_e32 v2, v241, v199
	global_load_dwordx4 v[210:213], v3, s[86:87] offset:384
	global_load_dwordx4 v[214:217], v3, s[86:87] offset:400
	global_load_dwordx4 v[218:221], v3, s[86:87] offset:416
	global_load_dwordx4 v[222:225], v3, s[86:87] offset:432
	global_load_dwordx4 v[226:229], v3, s[86:87] offset:448
	global_load_dwordx4 v[230:233], v3, s[86:87] offset:464
	global_load_dwordx4 v[234:237], v3, s[86:87] offset:480
	global_load_dwordx4 v[238:241], v3, s[86:87] offset:496
	global_load_dword v168, v[4:5], off offset:-2048
	global_load_dword v169, v[4:5], off offset:-1536
	global_load_dword v170, v[4:5], off offset:-1024
	global_load_dword v171, v[4:5], off offset:-512
	global_load_dword v172, v[4:5], off
	global_load_dword v173, v[4:5], off offset:512
	global_load_dword v174, v[4:5], off offset:1024
	global_load_dword v175, v[4:5], off offset:1536
	v_lshl_add_u64 v[4:5], v[4:5], 0, s[20:21]
	global_load_dword v176, v[4:5], off offset:-2048
	global_load_dword v177, v[4:5], off offset:-1536
	global_load_dword v178, v[4:5], off offset:-1024
	global_load_dword v179, v[4:5], off offset:-512
	global_load_dword v180, v[4:5], off
	global_load_dword v181, v[4:5], off offset:512
	global_load_dword v182, v[4:5], off offset:1024
	global_load_dword v183, v[4:5], off offset:1536
	v_lshl_add_u64 v[4:5], v[4:5], 0, s[20:21]
	global_load_dword v184, v[4:5], off offset:-2048
	global_load_dword v185, v[4:5], off offset:-1536
	global_load_dword v186, v[4:5], off offset:-1024
	global_load_dword v187, v[4:5], off offset:-512
	global_load_dword v188, v[4:5], off
	global_load_dword v189, v[4:5], off offset:512
	global_load_dword v190, v[4:5], off offset:1024
	global_load_dword v191, v[4:5], off offset:1536
	v_lshl_add_u64 v[4:5], v[4:5], 0, s[20:21]
	global_load_dword v192, v[4:5], off offset:-2048
	global_load_dword v193, v[4:5], off offset:-1536
	global_load_dword v194, v[4:5], off offset:-1024
	global_load_dword v195, v[4:5], off offset:-512
	global_load_dword v196, v[4:5], off
	global_load_dword v197, v[4:5], off offset:512
	global_load_dword v198, v[4:5], off offset:1024
	global_load_dword v199, v[4:5], off offset:1536
	v_lshl_add_u64 v[4:5], v[4:5], 0, s[20:21]
	s_waitcnt vmcnt(31)
	v_fmac_f32_e32 v2, v210, v168
	s_waitcnt vmcnt(30)
	v_fmac_f32_e32 v2, v211, v169
	s_waitcnt vmcnt(29)
	v_fmac_f32_e32 v2, v212, v170
	s_waitcnt vmcnt(28)
	v_fmac_f32_e32 v2, v213, v171
	s_waitcnt vmcnt(27)
	v_fmac_f32_e32 v2, v214, v172
	s_waitcnt vmcnt(26)
	v_fmac_f32_e32 v2, v215, v173
	s_waitcnt vmcnt(25)
	v_fmac_f32_e32 v2, v216, v174
	s_waitcnt vmcnt(24)
	v_fmac_f32_e32 v2, v217, v175
	s_waitcnt vmcnt(23)
	v_fmac_f32_e32 v2, v218, v176
	s_waitcnt vmcnt(22)
	v_fmac_f32_e32 v2, v219, v177
	s_waitcnt vmcnt(21)
	v_fmac_f32_e32 v2, v220, v178
	s_waitcnt vmcnt(20)
	v_fmac_f32_e32 v2, v221, v179
	s_waitcnt vmcnt(19)
	v_fmac_f32_e32 v2, v222, v180
	s_waitcnt vmcnt(18)
	v_fmac_f32_e32 v2, v223, v181
	s_waitcnt vmcnt(17)
	v_fmac_f32_e32 v2, v224, v182
	s_waitcnt vmcnt(16)
	v_fmac_f32_e32 v2, v225, v183
	s_waitcnt vmcnt(15)
	v_fmac_f32_e32 v2, v226, v184
	s_waitcnt vmcnt(14)
	v_fmac_f32_e32 v2, v227, v185
	s_waitcnt vmcnt(13)
	v_fmac_f32_e32 v2, v228, v186
	s_waitcnt vmcnt(12)
	v_fmac_f32_e32 v2, v229, v187
	s_waitcnt vmcnt(11)
	v_fmac_f32_e32 v2, v230, v188
	s_waitcnt vmcnt(10)
	v_fmac_f32_e32 v2, v231, v189
	s_waitcnt vmcnt(9)
	v_fmac_f32_e32 v2, v232, v190
	s_waitcnt vmcnt(8)
	v_fmac_f32_e32 v2, v233, v191
	s_waitcnt vmcnt(7)
	v_fmac_f32_e32 v2, v234, v192
	s_waitcnt vmcnt(6)
	v_fmac_f32_e32 v2, v235, v193
	s_waitcnt vmcnt(5)
	v_fmac_f32_e32 v2, v236, v194
	s_waitcnt vmcnt(4)
	v_fmac_f32_e32 v2, v237, v195
	s_waitcnt vmcnt(3)
	v_fmac_f32_e32 v2, v238, v196
	s_waitcnt vmcnt(2)
	v_fmac_f32_e32 v2, v239, v197
	s_waitcnt vmcnt(1)
	v_fmac_f32_e32 v2, v240, v198
	s_waitcnt vmcnt(0)
	v_fmac_f32_e32 v2, v241, v199
	s_mov_b64 s[22:23], 0x200
	s_add_i32 s16, s26, 0xffffccf0
	s_lshl_b32 s22, s16, 6
	s_lshl_b32 s23, s26, 7
	s_and_b32 s22, s22, 0xfffff800
	s_lshl_b32 s16, s16, 2
	s_and_b32 s23, s23, 0x780
	s_and_b32 s16, s16, 64
	s_or_b32 s22, s22, s23
	s_or_b32 s16, s22, s16
	s_addk_i32 s16, 0x1000
	v_add_u32_e32 v4, s16, v166
	v_ashrrev_i32_e32 v5, 31, v4
	v_lshl_add_u64 v[4:5], v[4:5], 2, s[4:5]
	s_mov_b64 s[22:23], 0
	global_store_dword v[4:5], v2, off
